# v46
# baseline (speedup 1.0000x reference)
.LBB0_479:
	s_or_b64 exec, exec, s[12:13]
	s_bitcmp1_b32 s31, 0
	v_and_b32_e32 v32, 64, v104
	s_cselect_b32 s12, 0x5180, 0
	v_add_u32_e32 v43, 64, v32
	v_xor_b32_e32 v32, 32, v104
	v_add_u32_e32 v37, s12, v72
	v_cmp_lt_i32_e64 s[12:13], v32, v43
	s_waitcnt vmcnt(47)
	v_lshlrev_b32_e32 v33, 16, v106
	s_waitcnt vmcnt(43)
	v_lshlrev_b32_e32 v34, 16, v112
	v_cndmask_b32_e64 v32, v104, v32, s[12:13]
	v_lshlrev_b32_e32 v38, 2, v32
	s_waitcnt vmcnt(40)
	v_lshlrev_b32_e32 v32, 16, v113
	v_sub_f32_e32 v32, 1.0, v32
	v_mul_f32_e32 v45, v32, v44
	v_rcp_f32_e32 v32, v45
	v_mul_f32_e32 v50, v45, v33
	v_add_f32_e32 v33, -1.0, v34
	v_lshlrev_b32_e32 v46, 16, v111
	v_lshlrev_b32_e32 v35, 16, v108
	s_waitcnt vmcnt(0)
	v_fma_f32 v47, v105, v33, 1.0
	v_pk_mul_f32 v[34:35], v[46:47], v[34:35]
	v_xor_b32_e32 v39, 16, v104
	v_pk_mul_f32 v[158:159], v[34:35], v[32:33] op_sel_hi:[1,0]
	v_cmp_lt_i32_e64 s[12:13], v39, v43
	v_pk_mul_f32 v[32:33], v[50:51], v[158:159] op_sel_hi:[0,1]
	ds_bpermute_b32 v32, v38, v32
	ds_bpermute_b32 v33, v38, v33
	v_cndmask_b32_e64 v34, v104, v39, s[12:13]
	v_lshlrev_b32_e32 v39, 2, v34
	v_xor_b32_e32 v40, 8, v104
	v_cmp_lt_i32_e64 s[12:13], v40, v43
	s_waitcnt lgkmcnt(0)
	v_pk_fma_f32 v[32:33], v[50:51], v[158:159], v[32:33] op_sel_hi:[0,1,1]
	ds_bpermute_b32 v34, v39, v32
	ds_bpermute_b32 v35, v39, v33
	v_cndmask_b32_e64 v40, v104, v40, s[12:13]
	v_lshlrev_b32_e32 v40, 2, v40
	v_xor_b32_e32 v41, 4, v104
	v_cmp_lt_i32_e64 s[12:13], v41, v43
	s_waitcnt lgkmcnt(0)
	v_pk_add_f32 v[32:33], v[32:33], v[34:35]
	s_nop 1
	v_add_f32_dpp v32, v32, v32 row_ror:8 row_mask:0xf bank_mask:0xf
	v_add_f32_dpp v33, v33, v33 row_ror:8 row_mask:0xf bank_mask:0xf
	v_cndmask_b32_e64 v41, v104, v41, s[12:13]
	v_lshlrev_b32_e32 v41, 2, v41
	v_xor_b32_e32 v42, 2, v104
	v_cmp_lt_i32_e64 s[12:13], v42, v43
	s_nop 1
	v_add_f32_dpp v32, v32, v32 row_ror:4 row_mask:0xf bank_mask:0xf
	v_add_f32_dpp v33, v33, v33 row_ror:4 row_mask:0xf bank_mask:0xf
	v_cndmask_b32_e64 v42, v104, v42, s[12:13]
	v_lshlrev_b32_e32 v42, 2, v42
	v_xor_b32_e32 v47, 1, v104
	v_cmp_lt_i32_e64 s[12:13], v47, v43
	s_nop 1
	v_add_f32_dpp v32, v32, v32 quad_perm:[2,3,0,1] row_mask:0xf bank_mask:0xf
	v_add_f32_dpp v33, v33, v33 quad_perm:[2,3,0,1] row_mask:0xf bank_mask:0xf
	v_cndmask_b32_e64 v43, v104, v47, s[12:13]
	v_lshlrev_b32_e32 v43, 2, v43
	v_lshl_add_u32 v36, v48, 2, v37
	v_lshlrev_b32_e32 v47, 16, v110
	s_nop 1
	v_add_f32_dpp v32, v32, v32 quad_perm:[1,0,3,2] row_mask:0xf bank_mask:0xf
	v_add_f32_dpp v33, v33, v33 quad_perm:[1,0,3,2] row_mask:0xf bank_mask:0xf
	v_add_u32_e32 v59, v36, v92
	v_mul_f32_e64 v44, v44, -v46
	ds_write_b32 v59, v47 offset:1024
	ds_write2st64_b32 v59, v44, v158 offset1:1
	ds_write2st64_b32 v59, v159, v50 offset0:2 offset1:3
	s_and_saveexec_b64 s[12:13], s[4:5]
	s_cbranch_execz .LBB0_481
	s_waitcnt lgkmcnt(3)
	v_add_u32_e32 v34, v37, v93
	ds_write_b64 v34, v[32:33] offset:20736
.LBB0_481:
	s_or_b64 exec, exec, s[12:13]
	v_lshlrev_b32_e32 v32, 16, v121
	v_sub_f32_e32 v32, 1.0, v32
	v_mul_f32_e32 v46, v32, v45
	v_lshlrev_b32_e32 v33, 16, v107
	v_rcp_f32_e32 v32, v46
	s_waitcnt lgkmcnt(4)
	v_lshlrev_b32_e32 v34, 16, v120
	v_mul_f32_e32 v50, v46, v33
	v_add_f32_e32 v33, -1.0, v34
	v_lshlrev_b32_e32 v158, 16, v118
	s_waitcnt lgkmcnt(3)
	v_lshlrev_b32_e32 v35, 16, v109
	v_fma_f32 v159, v105, v33, 1.0
	v_pk_mul_f32 v[34:35], v[158:159], v[34:35]
	v_lshlrev_b32_e32 v47, 16, v116
	v_pk_mul_f32 v[162:163], v[34:35], v[32:33] op_sel_hi:[1,0]
	v_add_u32_e32 v44, v36, v94
	v_pk_mul_f32 v[32:33], v[50:51], v[162:163] op_sel_hi:[0,1]
	ds_bpermute_b32 v32, v38, v32
	ds_bpermute_b32 v33, v38, v33
	v_mul_f32_e64 v45, v45, -v158
	ds_write_b32 v44, v47 offset:1024
	ds_write2st64_b32 v44, v45, v162 offset1:1
	ds_write2st64_b32 v44, v163, v50 offset0:2 offset1:3
	s_waitcnt lgkmcnt(3)
	v_pk_fma_f32 v[32:33], v[50:51], v[162:163], v[32:33] op_sel_hi:[0,1,1]
	ds_bpermute_b32 v34, v39, v32
	ds_bpermute_b32 v35, v39, v33
	s_waitcnt lgkmcnt(0)
	v_pk_add_f32 v[32:33], v[32:33], v[34:35]
	s_nop 1
	v_add_f32_dpp v32, v32, v32 row_ror:8 row_mask:0xf bank_mask:0xf
	v_add_f32_dpp v33, v33, v33 row_ror:8 row_mask:0xf bank_mask:0xf
	s_nop 0
	v_add_f32_dpp v32, v32, v32 row_ror:4 row_mask:0xf bank_mask:0xf
	v_add_f32_dpp v33, v33, v33 row_ror:4 row_mask:0xf bank_mask:0xf
	s_nop 0
	v_add_f32_dpp v32, v32, v32 quad_perm:[2,3,0,1] row_mask:0xf bank_mask:0xf
	v_add_f32_dpp v33, v33, v33 quad_perm:[2,3,0,1] row_mask:0xf bank_mask:0xf
	s_nop 0
	v_add_f32_dpp v32, v32, v32 quad_perm:[1,0,3,2] row_mask:0xf bank_mask:0xf
	v_add_f32_dpp v33, v33, v33 quad_perm:[1,0,3,2] row_mask:0xf bank_mask:0xf
	s_and_saveexec_b64 s[12:13], s[4:5]
	s_cbranch_execz .LBB0_483
	s_waitcnt lgkmcnt(0)
	v_add_u32_e32 v34, v37, v95
	ds_write_b64 v34, v[32:33] offset:20736
.LBB0_483:
	s_or_b64 exec, exec, s[12:13]
	v_lshlrev_b32_e32 v32, 16, v129
	v_sub_f32_e32 v32, 1.0, v32
	v_mul_f32_e32 v45, v32, v46
	v_lshlrev_b32_e32 v33, 16, v114
	v_rcp_f32_e32 v32, v45
	s_waitcnt lgkmcnt(1)
	v_lshlrev_b32_e32 v34, 16, v126
	v_mul_f32_e32 v50, v45, v33
	v_add_f32_e32 v33, -1.0, v34
	v_lshlrev_b32_e32 v158, 16, v119
	s_waitcnt lgkmcnt(0)
	v_lshlrev_b32_e32 v35, 16, v115
	v_fma_f32 v159, v105, v33, 1.0
	v_pk_mul_f32 v[34:35], v[158:159], v[34:35]
	v_lshlrev_b32_e32 v47, 16, v117
	v_pk_mul_f32 v[162:163], v[34:35], v[32:33] op_sel_hi:[1,0]
	v_mul_f32_e64 v46, v46, -v158
	v_pk_mul_f32 v[32:33], v[50:51], v[162:163] op_sel_hi:[0,1]
	ds_bpermute_b32 v32, v38, v32
	ds_bpermute_b32 v33, v38, v33
	ds_write_b32 v44, v47 offset:2304
	ds_write2st64_b32 v44, v46, v162 offset0:5 offset1:6
	ds_write2st64_b32 v44, v163, v50 offset0:7 offset1:8
	s_waitcnt lgkmcnt(3)
	v_pk_fma_f32 v[32:33], v[50:51], v[162:163], v[32:33] op_sel_hi:[0,1,1]
	ds_bpermute_b32 v34, v39, v32
	ds_bpermute_b32 v35, v39, v33
	s_waitcnt lgkmcnt(0)
	v_pk_add_f32 v[32:33], v[32:33], v[34:35]
	s_nop 1
	v_add_f32_dpp v32, v32, v32 row_ror:8 row_mask:0xf bank_mask:0xf
	v_add_f32_dpp v33, v33, v33 row_ror:8 row_mask:0xf bank_mask:0xf
	s_nop 0
	v_add_f32_dpp v32, v32, v32 row_ror:4 row_mask:0xf bank_mask:0xf
	v_add_f32_dpp v33, v33, v33 row_ror:4 row_mask:0xf bank_mask:0xf
	s_nop 0
	v_add_f32_dpp v32, v32, v32 quad_perm:[2,3,0,1] row_mask:0xf bank_mask:0xf
	v_add_f32_dpp v33, v33, v33 quad_perm:[2,3,0,1] row_mask:0xf bank_mask:0xf
	s_nop 0
	v_add_f32_dpp v32, v32, v32 quad_perm:[1,0,3,2] row_mask:0xf bank_mask:0xf
	v_add_f32_dpp v33, v33, v33 quad_perm:[1,0,3,2] row_mask:0xf bank_mask:0xf
	s_and_saveexec_b64 s[12:13], s[4:5]
	s_cbranch_execz .LBB0_485
	s_waitcnt lgkmcnt(0)
	v_add_u32_e32 v34, v37, v96
	ds_write_b64 v34, v[32:33] offset:20736
.LBB0_485:
	s_or_b64 exec, exec, s[12:13]
	v_lshlrev_b32_e32 v32, 16, v128
	v_sub_f32_e32 v32, 1.0, v32
	v_mul_f32_e32 v46, v32, v45
	v_lshlrev_b32_e32 v33, 16, v122
	v_rcp_f32_e32 v32, v46
	s_waitcnt lgkmcnt(1)
	v_lshlrev_b32_e32 v34, 16, v127
	v_mul_f32_e32 v50, v46, v33
	v_add_f32_e32 v33, -1.0, v34
	v_lshlrev_b32_e32 v158, 16, v125
	s_waitcnt lgkmcnt(0)
	v_lshlrev_b32_e32 v35, 16, v123
	v_fma_f32 v159, v105, v33, 1.0
	v_pk_mul_f32 v[34:35], v[158:159], v[34:35]
	v_lshlrev_b32_e32 v47, 16, v124
	v_pk_mul_f32 v[162:163], v[34:35], v[32:33] op_sel_hi:[1,0]
	v_mul_f32_e64 v45, v45, -v158
	v_pk_mul_f32 v[32:33], v[50:51], v[162:163] op_sel_hi:[0,1]
	ds_bpermute_b32 v32, v38, v32
	ds_bpermute_b32 v33, v38, v33
	ds_write_b32 v44, v47 offset:3584
	ds_write2st64_b32 v44, v45, v162 offset0:10 offset1:11
	ds_write2st64_b32 v44, v163, v50 offset0:12 offset1:13
	s_waitcnt lgkmcnt(3)
	v_pk_fma_f32 v[32:33], v[50:51], v[162:163], v[32:33] op_sel_hi:[0,1,1]
	ds_bpermute_b32 v34, v39, v32
	ds_bpermute_b32 v35, v39, v33
	s_waitcnt lgkmcnt(0)
	v_pk_add_f32 v[32:33], v[32:33], v[34:35]
	s_nop 1
	v_add_f32_dpp v32, v32, v32 row_ror:8 row_mask:0xf bank_mask:0xf
	v_add_f32_dpp v33, v33, v33 row_ror:8 row_mask:0xf bank_mask:0xf
	s_nop 0
	v_add_f32_dpp v32, v32, v32 row_ror:4 row_mask:0xf bank_mask:0xf
	v_add_f32_dpp v33, v33, v33 row_ror:4 row_mask:0xf bank_mask:0xf
	s_nop 0
	v_add_f32_dpp v32, v32, v32 quad_perm:[2,3,0,1] row_mask:0xf bank_mask:0xf
	v_add_f32_dpp v33, v33, v33 quad_perm:[2,3,0,1] row_mask:0xf bank_mask:0xf
	s_nop 0
	v_add_f32_dpp v32, v32, v32 quad_perm:[1,0,3,2] row_mask:0xf bank_mask:0xf
	v_add_f32_dpp v33, v33, v33 quad_perm:[1,0,3,2] row_mask:0xf bank_mask:0xf
	s_and_saveexec_b64 s[12:13], s[4:5]
	s_cbranch_execz .LBB0_487
	s_waitcnt lgkmcnt(0)
	v_add_u32_e32 v34, v37, v97
	ds_write_b64 v34, v[32:33] offset:20736
.LBB0_487:
	s_or_b64 exec, exec, s[12:13]
	v_lshlrev_b32_e32 v32, 16, v137
	v_sub_f32_e32 v32, 1.0, v32
	v_mul_f32_e32 v45, v32, v46
	v_lshlrev_b32_e32 v33, 16, v130
	v_rcp_f32_e32 v32, v45
	s_waitcnt lgkmcnt(1)
	v_lshlrev_b32_e32 v34, 16, v136
	v_mul_f32_e32 v50, v45, v33
	v_add_f32_e32 v33, -1.0, v34
	v_lshlrev_b32_e32 v158, 16, v135
	s_waitcnt lgkmcnt(0)
	v_lshlrev_b32_e32 v35, 16, v132
	v_fma_f32 v159, v105, v33, 1.0
	v_pk_mul_f32 v[34:35], v[158:159], v[34:35]
	v_lshlrev_b32_e32 v47, 16, v134
	v_pk_mul_f32 v[162:163], v[34:35], v[32:33] op_sel_hi:[1,0]
	v_mul_f32_e64 v46, v46, -v158
	v_pk_mul_f32 v[32:33], v[50:51], v[162:163] op_sel_hi:[0,1]
	ds_bpermute_b32 v32, v38, v32
	ds_bpermute_b32 v33, v38, v33
	ds_write_b32 v44, v47 offset:4864
	ds_write2st64_b32 v44, v46, v162 offset0:15 offset1:16
	ds_write2st64_b32 v44, v163, v50 offset0:17 offset1:18
	s_waitcnt lgkmcnt(3)
	v_pk_fma_f32 v[32:33], v[50:51], v[162:163], v[32:33] op_sel_hi:[0,1,1]
	ds_bpermute_b32 v34, v39, v32
	ds_bpermute_b32 v35, v39, v33
	s_waitcnt lgkmcnt(0)
	v_pk_add_f32 v[32:33], v[32:33], v[34:35]
	s_nop 1
	v_add_f32_dpp v32, v32, v32 row_ror:8 row_mask:0xf bank_mask:0xf
	v_add_f32_dpp v33, v33, v33 row_ror:8 row_mask:0xf bank_mask:0xf
	s_nop 0
	v_add_f32_dpp v32, v32, v32 row_ror:4 row_mask:0xf bank_mask:0xf
	v_add_f32_dpp v33, v33, v33 row_ror:4 row_mask:0xf bank_mask:0xf
	s_nop 0
	v_add_f32_dpp v32, v32, v32 quad_perm:[2,3,0,1] row_mask:0xf bank_mask:0xf
	v_add_f32_dpp v33, v33, v33 quad_perm:[2,3,0,1] row_mask:0xf bank_mask:0xf
	s_nop 0
	v_add_f32_dpp v32, v32, v32 quad_perm:[1,0,3,2] row_mask:0xf bank_mask:0xf
	v_add_f32_dpp v33, v33, v33 quad_perm:[1,0,3,2] row_mask:0xf bank_mask:0xf
	s_and_saveexec_b64 s[12:13], s[4:5]
	s_cbranch_execz .LBB0_489
	s_waitcnt lgkmcnt(0)
	v_add_u32_e32 v34, v37, v98
	ds_write_b64 v34, v[32:33] offset:20736
.LBB0_489:
	s_or_b64 exec, exec, s[12:13]
	v_lshlrev_b32_e32 v32, 16, v145
	v_sub_f32_e32 v32, 1.0, v32
	v_mul_f32_e32 v46, v32, v45
	v_lshlrev_b32_e32 v33, 16, v131
	v_rcp_f32_e32 v32, v46
	s_waitcnt lgkmcnt(1)
	v_lshlrev_b32_e32 v34, 16, v144
	v_mul_f32_e32 v50, v46, v33
	v_add_f32_e32 v33, -1.0, v34
	v_lshlrev_b32_e32 v158, 16, v142
	s_waitcnt lgkmcnt(0)
	v_lshlrev_b32_e32 v35, 16, v133
	v_fma_f32 v159, v105, v33, 1.0
	v_pk_mul_f32 v[34:35], v[158:159], v[34:35]
	v_lshlrev_b32_e32 v47, 16, v140
	v_pk_mul_f32 v[162:163], v[34:35], v[32:33] op_sel_hi:[1,0]
	v_mul_f32_e64 v45, v45, -v158
	v_pk_mul_f32 v[32:33], v[50:51], v[162:163] op_sel_hi:[0,1]
	ds_bpermute_b32 v32, v38, v32
	ds_bpermute_b32 v33, v38, v33
	ds_write_b32 v44, v47 offset:6144
	ds_write2st64_b32 v44, v45, v162 offset0:20 offset1:21
	ds_write2st64_b32 v44, v163, v50 offset0:22 offset1:23
	s_waitcnt lgkmcnt(3)
	v_pk_fma_f32 v[32:33], v[50:51], v[162:163], v[32:33] op_sel_hi:[0,1,1]
	ds_bpermute_b32 v34, v39, v32
	ds_bpermute_b32 v35, v39, v33
	s_waitcnt lgkmcnt(0)
	v_pk_add_f32 v[32:33], v[32:33], v[34:35]
	s_nop 1
	v_add_f32_dpp v32, v32, v32 row_ror:8 row_mask:0xf bank_mask:0xf
	v_add_f32_dpp v33, v33, v33 row_ror:8 row_mask:0xf bank_mask:0xf
	s_nop 0
	v_add_f32_dpp v32, v32, v32 row_ror:4 row_mask:0xf bank_mask:0xf
	v_add_f32_dpp v33, v33, v33 row_ror:4 row_mask:0xf bank_mask:0xf
	s_nop 0
	v_add_f32_dpp v32, v32, v32 quad_perm:[2,3,0,1] row_mask:0xf bank_mask:0xf
	v_add_f32_dpp v33, v33, v33 quad_perm:[2,3,0,1] row_mask:0xf bank_mask:0xf
	s_nop 0
	v_add_f32_dpp v32, v32, v32 quad_perm:[1,0,3,2] row_mask:0xf bank_mask:0xf
	v_add_f32_dpp v33, v33, v33 quad_perm:[1,0,3,2] row_mask:0xf bank_mask:0xf
	s_and_saveexec_b64 s[12:13], s[4:5]
	s_cbranch_execz .LBB0_491
	s_waitcnt lgkmcnt(0)
	v_add_u32_e32 v34, v37, v99
	ds_write_b64 v34, v[32:33] offset:20736
.LBB0_491:
	s_or_b64 exec, exec, s[12:13]
	v_lshlrev_b32_e32 v32, 16, v153
	v_sub_f32_e32 v32, 1.0, v32
	v_mul_f32_e32 v45, v32, v46
	v_lshlrev_b32_e32 v33, 16, v138
	v_rcp_f32_e32 v32, v45
	s_waitcnt lgkmcnt(1)
	v_lshlrev_b32_e32 v34, 16, v150
	v_mul_f32_e32 v50, v45, v33
	v_add_f32_e32 v33, -1.0, v34
	v_lshlrev_b32_e32 v158, 16, v143
	s_waitcnt lgkmcnt(0)
	v_lshlrev_b32_e32 v35, 16, v139
	v_fma_f32 v159, v105, v33, 1.0
	v_pk_mul_f32 v[34:35], v[158:159], v[34:35]
	v_lshlrev_b32_e32 v47, 16, v141
	v_pk_mul_f32 v[162:163], v[34:35], v[32:33] op_sel_hi:[1,0]
	v_mul_f32_e64 v46, v46, -v158
	v_pk_mul_f32 v[32:33], v[50:51], v[162:163] op_sel_hi:[0,1]
	ds_bpermute_b32 v32, v38, v32
	ds_bpermute_b32 v33, v38, v33
	ds_write_b32 v44, v47 offset:7424
	ds_write2st64_b32 v44, v46, v162 offset0:25 offset1:26
	ds_write2st64_b32 v44, v163, v50 offset0:27 offset1:28
	s_waitcnt lgkmcnt(3)
	v_pk_fma_f32 v[32:33], v[50:51], v[162:163], v[32:33] op_sel_hi:[0,1,1]
	ds_bpermute_b32 v34, v39, v32
	ds_bpermute_b32 v35, v39, v33
	s_waitcnt lgkmcnt(0)
	v_pk_add_f32 v[32:33], v[32:33], v[34:35]
	s_nop 1
	v_add_f32_dpp v32, v32, v32 row_ror:8 row_mask:0xf bank_mask:0xf
	v_add_f32_dpp v33, v33, v33 row_ror:8 row_mask:0xf bank_mask:0xf
	s_nop 0
	v_add_f32_dpp v32, v32, v32 row_ror:4 row_mask:0xf bank_mask:0xf
	v_add_f32_dpp v33, v33, v33 row_ror:4 row_mask:0xf bank_mask:0xf
	s_nop 0
	v_add_f32_dpp v32, v32, v32 quad_perm:[2,3,0,1] row_mask:0xf bank_mask:0xf
	v_add_f32_dpp v33, v33, v33 quad_perm:[2,3,0,1] row_mask:0xf bank_mask:0xf
	s_nop 0
	v_add_f32_dpp v32, v32, v32 quad_perm:[1,0,3,2] row_mask:0xf bank_mask:0xf
	v_add_f32_dpp v33, v33, v33 quad_perm:[1,0,3,2] row_mask:0xf bank_mask:0xf
	s_and_saveexec_b64 s[12:13], s[4:5]
	s_cbranch_execz .LBB0_493
	s_waitcnt lgkmcnt(0)
	v_add_u32_e32 v34, v37, v100
	ds_write_b64 v34, v[32:33] offset:20736
.LBB0_493:
	s_or_b64 exec, exec, s[12:13]
	v_lshlrev_b32_e32 v32, 16, v152
	v_sub_f32_e32 v32, 1.0, v32
	v_mul_f32_e32 v46, v32, v45
	v_lshlrev_b32_e32 v33, 16, v146
	v_rcp_f32_e32 v32, v46
	s_waitcnt lgkmcnt(1)
	v_lshlrev_b32_e32 v34, 16, v151
	v_mul_f32_e32 v50, v46, v33
	v_add_f32_e32 v33, -1.0, v34
	v_lshlrev_b32_e32 v158, 16, v149
	s_waitcnt lgkmcnt(0)
	v_lshlrev_b32_e32 v35, 16, v147
	v_fma_f32 v159, v105, v33, 1.0
	v_pk_mul_f32 v[34:35], v[158:159], v[34:35]
	s_nop 0
	v_pk_mul_f32 v[162:163], v[34:35], v[32:33] op_sel_hi:[1,0]
	s_nop 0
	v_pk_mul_f32 v[32:33], v[50:51], v[162:163] op_sel_hi:[0,1]
	ds_bpermute_b32 v32, v38, v32
	ds_bpermute_b32 v33, v38, v33
	v_lshlrev_b32_e32 v38, 16, v148
	s_waitcnt lgkmcnt(0)
	v_pk_fma_f32 v[32:33], v[50:51], v[162:163], v[32:33] op_sel_hi:[0,1,1]
	ds_bpermute_b32 v34, v39, v32
	ds_bpermute_b32 v35, v39, v33
	v_mul_f32_e64 v39, v45, -v158
	ds_write_b32 v44, v38 offset:8704
	ds_write2st64_b32 v44, v39, v162 offset0:30 offset1:31
	ds_write2st64_b32 v44, v163, v50 offset0:32 offset1:33
	s_waitcnt lgkmcnt(3)
	v_pk_add_f32 v[32:33], v[32:33], v[34:35]
	s_nop 1
	v_add_f32_dpp v32, v32, v32 row_ror:8 row_mask:0xf bank_mask:0xf
	v_add_f32_dpp v33, v33, v33 row_ror:8 row_mask:0xf bank_mask:0xf
	s_waitcnt lgkmcnt(0)
	s_nop 1
	v_add_f32_dpp v32, v32, v32 row_ror:4 row_mask:0xf bank_mask:0xf
	v_add_f32_dpp v33, v33, v33 row_ror:4 row_mask:0xf bank_mask:0xf
	s_nop 0
	v_add_f32_dpp v32, v32, v32 quad_perm:[2,3,0,1] row_mask:0xf bank_mask:0xf
	v_add_f32_dpp v33, v33, v33 quad_perm:[2,3,0,1] row_mask:0xf bank_mask:0xf
	s_nop 0
	v_add_f32_dpp v32, v32, v32 quad_perm:[1,0,3,2] row_mask:0xf bank_mask:0xf
	v_add_f32_dpp v33, v33, v33 quad_perm:[1,0,3,2] row_mask:0xf bank_mask:0xf
	s_and_saveexec_b64 s[12:13], s[4:5]
	s_cbranch_execz .LBB0_496
	s_waitcnt lgkmcnt(0)
	v_add_u32_e32 v34, v37, v101
	ds_write_b64 v34, v[32:33] offset:20736
	s_or_b64 exec, exec, s[12:13]
	s_and_saveexec_b64 s[12:13], s[10:11]
	s_cbranch_execnz .LBB0_497
